# silupk
# speedup vs baseline: 1.0032x; 1.0032x over previous
.LBB0_435:
	v_mov_b32_e32 v184, 0xbfb8aa3b
	v_pk_mul_f32 v[176:177], v[126:127], v[184:185] op_sel_hi:[1,0]
	v_pk_mul_f32 v[178:179], v[128:129], v[184:185] op_sel_hi:[1,0]
	v_pk_mul_f32 v[180:181], v[118:119], v[184:185] op_sel_hi:[1,0]
	v_pk_mul_f32 v[182:183], v[120:121], v[184:185] op_sel_hi:[1,0]
	v_exp_f32_e32 v176, v176
	v_exp_f32_e32 v177, v177
	v_exp_f32_e32 v178, v178
	v_exp_f32_e32 v179, v179
	v_exp_f32_e32 v180, v180
	v_exp_f32_e32 v181, v181
	v_exp_f32_e32 v182, v182
	v_exp_f32_e32 v183, v183
	v_pk_add_f32 v[176:177], v[176:177], 1.0 op_sel_hi:[1,0]
	v_pk_add_f32 v[178:179], v[178:179], 1.0 op_sel_hi:[1,0]
	v_pk_add_f32 v[180:181], v[180:181], 1.0 op_sel_hi:[1,0]
	v_pk_add_f32 v[182:183], v[182:183], 1.0 op_sel_hi:[1,0]
	v_rcp_f32_e32 v176, v176
	v_rcp_f32_e32 v177, v177
	v_rcp_f32_e32 v178, v178
	v_rcp_f32_e32 v179, v179
	v_rcp_f32_e32 v180, v180
	v_rcp_f32_e32 v181, v181
	v_rcp_f32_e32 v182, v182
	v_rcp_f32_e32 v183, v183
	v_pk_mul_f32 v[176:177], v[126:127], v[176:177]
	v_pk_mul_f32 v[178:179], v[128:129], v[178:179]
	v_pk_mul_f32 v[180:181], v[118:119], v[180:181]
	v_pk_mul_f32 v[182:183], v[120:121], v[182:183]
	s_lshl_b32 s6, s48, 8
	v_add_u32_e32 v154, s6, v144
	v_mov_b64_e32 v[142:143], s[22:23]
	v_mad_i64_i32 v[154:155], s[48:49], v154, s16, v[142:143]
	s_lshl_b32 s48, s9, 7
	v_mul_f32_e32 v122, v176, v122
	s_ashr_i32 s49, s48, 31
	s_lshl_b64 s[48:49], s[48:49], 1
	v_lshl_add_u64 v[154:155], v[154:155], 0, s[48:49]
	v_lshl_add_u64 v[154:155], v[154:155], 0, s[26:27]
	v_readlane_b32 s80, v254, 35
	s_andn2_b64 vcc, exec, s[38:39]
	v_mul_f32_e32 v123, v177, v123
	v_readlane_b32 s81, v254, 36
	v_readlane_b32 s82, v254, 37
	v_readlane_b32 s83, v254, 38
	v_readlane_b32 s84, v254, 39
	v_readlane_b32 s85, v254, 40
	v_readlane_b32 s86, v254, 41
	v_mul_f32_e32 v124, v178, v124
	v_readlane_b32 s87, v254, 42
	v_readlane_b32 s88, v254, 43
	v_readlane_b32 s89, v254, 44
	v_readlane_b32 s90, v254, 45
	v_readlane_b32 s91, v254, 46
	v_readlane_b32 s92, v254, 47
	v_mul_f32_e32 v125, v179, v125
	v_readlane_b32 s93, v254, 48
	v_readlane_b32 s94, v254, 49
	v_readlane_b32 s95, v254, 50
	v_mul_f32_e32 v126, v180, v114
	v_mul_f32_e32 v127, v181, v115
	v_lshl_add_u64 v[118:119], v[154:155], 0, v[0:1]
	v_mul_f32_e32 v120, v182, v116
	v_mul_f32_e32 v117, v183, v117
	v_cvt_pk_bf16_f32 v114, v122, v123
	v_cvt_pk_bf16_f32 v115, v124, v125
	v_cvt_pk_bf16_f32 v116, v126, v127
	v_cvt_pk_bf16_f32 v117, v120, v117
	global_store_dwordx4 v[118:119], v[114:117], off
	s_nop 1
	v_pk_mul_f32 v[176:177], v[110:111], v[184:185] op_sel_hi:[1,0]
	v_pk_mul_f32 v[178:179], v[112:113], v[184:185] op_sel_hi:[1,0]
	v_pk_mul_f32 v[180:181], v[102:103], v[184:185] op_sel_hi:[1,0]
	v_pk_mul_f32 v[182:183], v[104:105], v[184:185] op_sel_hi:[1,0]
	v_exp_f32_e32 v176, v176
	v_exp_f32_e32 v177, v177
	v_exp_f32_e32 v178, v178
	v_exp_f32_e32 v179, v179
	v_exp_f32_e32 v180, v180
	v_exp_f32_e32 v181, v181
	v_exp_f32_e32 v182, v182
	v_exp_f32_e32 v183, v183
	v_pk_add_f32 v[176:177], v[176:177], 1.0 op_sel_hi:[1,0]
	v_pk_add_f32 v[178:179], v[178:179], 1.0 op_sel_hi:[1,0]
	v_pk_add_f32 v[180:181], v[180:181], 1.0 op_sel_hi:[1,0]
	v_pk_add_f32 v[182:183], v[182:183], 1.0 op_sel_hi:[1,0]
	v_rcp_f32_e32 v176, v176
	v_rcp_f32_e32 v177, v177
	v_rcp_f32_e32 v178, v178
	v_rcp_f32_e32 v179, v179
	v_rcp_f32_e32 v180, v180
	v_rcp_f32_e32 v181, v181
	v_rcp_f32_e32 v182, v182
	v_rcp_f32_e32 v183, v183
	v_pk_mul_f32 v[176:177], v[110:111], v[176:177]
	v_pk_mul_f32 v[178:179], v[112:113], v[178:179]
	v_pk_mul_f32 v[180:181], v[102:103], v[180:181]
	v_pk_mul_f32 v[182:183], v[104:105], v[182:183]
	v_add_u32_e32 v114, s6, v146
	v_mad_i64_i32 v[114:115], s[50:51], v114, s16, v[142:143]
	v_lshl_add_u64 v[114:115], v[114:115], 0, s[48:49]
	v_lshl_add_u64 v[114:115], v[114:115], 0, s[26:27]
	v_mul_f32_e32 v106, v176, v106
	v_mul_f32_e32 v107, v177, v107
	v_mul_f32_e32 v108, v178, v108
	v_mul_f32_e32 v109, v179, v109
	v_mul_f32_e32 v110, v180, v98
	v_mul_f32_e32 v111, v181, v99
	v_lshl_add_u64 v[102:103], v[114:115], 0, v[0:1]
	v_mul_f32_e32 v104, v182, v100
	v_mul_f32_e32 v101, v183, v101
	v_cvt_pk_bf16_f32 v98, v106, v107
	v_cvt_pk_bf16_f32 v99, v108, v109
	v_cvt_pk_bf16_f32 v100, v110, v111
	v_cvt_pk_bf16_f32 v101, v104, v101
	global_store_dwordx4 v[102:103], v[98:101], off
	s_nop 1
	v_pk_mul_f32 v[176:177], v[94:95], v[184:185] op_sel_hi:[1,0]
	v_pk_mul_f32 v[178:179], v[96:97], v[184:185] op_sel_hi:[1,0]
	v_pk_mul_f32 v[180:181], v[86:87], v[184:185] op_sel_hi:[1,0]
	v_pk_mul_f32 v[182:183], v[88:89], v[184:185] op_sel_hi:[1,0]
	v_exp_f32_e32 v176, v176
	v_exp_f32_e32 v177, v177
	v_exp_f32_e32 v178, v178
	v_exp_f32_e32 v179, v179
	v_exp_f32_e32 v180, v180
	v_exp_f32_e32 v181, v181
	v_exp_f32_e32 v182, v182
	v_exp_f32_e32 v183, v183
	v_pk_add_f32 v[176:177], v[176:177], 1.0 op_sel_hi:[1,0]
	v_pk_add_f32 v[178:179], v[178:179], 1.0 op_sel_hi:[1,0]
	v_pk_add_f32 v[180:181], v[180:181], 1.0 op_sel_hi:[1,0]
	v_pk_add_f32 v[182:183], v[182:183], 1.0 op_sel_hi:[1,0]
	v_rcp_f32_e32 v176, v176
	v_rcp_f32_e32 v177, v177
	v_rcp_f32_e32 v178, v178
	v_rcp_f32_e32 v179, v179
	v_rcp_f32_e32 v180, v180
	v_rcp_f32_e32 v181, v181
	v_rcp_f32_e32 v182, v182
	v_rcp_f32_e32 v183, v183
	v_pk_mul_f32 v[176:177], v[94:95], v[176:177]
	v_pk_mul_f32 v[178:179], v[96:97], v[178:179]
	v_pk_mul_f32 v[180:181], v[86:87], v[180:181]
	v_pk_mul_f32 v[182:183], v[88:89], v[182:183]
	v_add_u32_e32 v98, s6, v147
	v_mad_i64_i32 v[98:99], s[50:51], v98, s16, v[142:143]
	v_lshl_add_u64 v[98:99], v[98:99], 0, s[48:49]
	v_lshl_add_u64 v[98:99], v[98:99], 0, s[26:27]
	v_mul_f32_e32 v90, v176, v90
	v_mul_f32_e32 v91, v177, v91
	v_mul_f32_e32 v92, v178, v92
	v_mul_f32_e32 v93, v179, v93
	v_mul_f32_e32 v94, v180, v82
	v_mul_f32_e32 v95, v181, v83
	v_lshl_add_u64 v[86:87], v[98:99], 0, v[0:1]
	v_mul_f32_e32 v88, v182, v84
	v_mul_f32_e32 v85, v183, v85
	v_cvt_pk_bf16_f32 v82, v90, v91
	v_cvt_pk_bf16_f32 v83, v92, v93
	v_cvt_pk_bf16_f32 v84, v94, v95
	v_cvt_pk_bf16_f32 v85, v88, v85
	global_store_dwordx4 v[86:87], v[82:85], off
	s_nop 1
	v_pk_mul_f32 v[176:177], v[78:79], v[184:185] op_sel_hi:[1,0]
	v_pk_mul_f32 v[178:179], v[80:81], v[184:185] op_sel_hi:[1,0]
	v_pk_mul_f32 v[180:181], v[70:71], v[184:185] op_sel_hi:[1,0]
	v_pk_mul_f32 v[182:183], v[72:73], v[184:185] op_sel_hi:[1,0]
	v_exp_f32_e32 v176, v176
	v_exp_f32_e32 v177, v177
	v_exp_f32_e32 v178, v178
	v_exp_f32_e32 v179, v179
	v_exp_f32_e32 v180, v180
	v_exp_f32_e32 v181, v181
	v_exp_f32_e32 v182, v182
	v_exp_f32_e32 v183, v183
	v_pk_add_f32 v[176:177], v[176:177], 1.0 op_sel_hi:[1,0]
	v_pk_add_f32 v[178:179], v[178:179], 1.0 op_sel_hi:[1,0]
	v_pk_add_f32 v[180:181], v[180:181], 1.0 op_sel_hi:[1,0]
	v_pk_add_f32 v[182:183], v[182:183], 1.0 op_sel_hi:[1,0]
	v_rcp_f32_e32 v176, v176
	v_rcp_f32_e32 v177, v177
	v_rcp_f32_e32 v178, v178
	v_rcp_f32_e32 v179, v179
	v_rcp_f32_e32 v180, v180
	v_rcp_f32_e32 v181, v181
	v_rcp_f32_e32 v182, v182
	v_rcp_f32_e32 v183, v183
	v_pk_mul_f32 v[176:177], v[78:79], v[176:177]
	v_pk_mul_f32 v[178:179], v[80:81], v[178:179]
	v_pk_mul_f32 v[180:181], v[70:71], v[180:181]
	v_pk_mul_f32 v[182:183], v[72:73], v[182:183]
	v_add_u32_e32 v82, s6, v148
	v_mad_i64_i32 v[82:83], s[50:51], v82, s16, v[142:143]
	v_lshl_add_u64 v[82:83], v[82:83], 0, s[48:49]
	v_lshl_add_u64 v[82:83], v[82:83], 0, s[26:27]
	v_mul_f32_e32 v74, v176, v74
	v_mul_f32_e32 v75, v177, v75
	v_mul_f32_e32 v76, v178, v76
	v_mul_f32_e32 v77, v179, v77
	v_mul_f32_e32 v78, v180, v66
	v_mul_f32_e32 v79, v181, v67
	v_lshl_add_u64 v[70:71], v[82:83], 0, v[0:1]
	v_mul_f32_e32 v72, v182, v68
	v_mul_f32_e32 v69, v183, v69
	v_cvt_pk_bf16_f32 v66, v74, v75
	v_cvt_pk_bf16_f32 v67, v76, v77
	v_cvt_pk_bf16_f32 v68, v78, v79
	v_cvt_pk_bf16_f32 v69, v72, v69
	global_store_dwordx4 v[70:71], v[66:69], off
	s_nop 1
	v_pk_mul_f32 v[176:177], v[62:63], v[184:185] op_sel_hi:[1,0]
	v_pk_mul_f32 v[178:179], v[64:65], v[184:185] op_sel_hi:[1,0]
	v_pk_mul_f32 v[180:181], v[54:55], v[184:185] op_sel_hi:[1,0]
	v_pk_mul_f32 v[182:183], v[56:57], v[184:185] op_sel_hi:[1,0]
	v_exp_f32_e32 v176, v176
	v_exp_f32_e32 v177, v177
	v_exp_f32_e32 v178, v178
	v_exp_f32_e32 v179, v179
	v_exp_f32_e32 v180, v180
	v_exp_f32_e32 v181, v181
	v_exp_f32_e32 v182, v182
	v_exp_f32_e32 v183, v183
	v_pk_add_f32 v[176:177], v[176:177], 1.0 op_sel_hi:[1,0]
	v_pk_add_f32 v[178:179], v[178:179], 1.0 op_sel_hi:[1,0]
	v_pk_add_f32 v[180:181], v[180:181], 1.0 op_sel_hi:[1,0]
	v_pk_add_f32 v[182:183], v[182:183], 1.0 op_sel_hi:[1,0]
	v_rcp_f32_e32 v176, v176
	v_rcp_f32_e32 v177, v177
	v_rcp_f32_e32 v178, v178
	v_rcp_f32_e32 v179, v179
	v_rcp_f32_e32 v180, v180
	v_rcp_f32_e32 v181, v181
	v_rcp_f32_e32 v182, v182
	v_rcp_f32_e32 v183, v183
	v_pk_mul_f32 v[176:177], v[62:63], v[176:177]
	v_pk_mul_f32 v[178:179], v[64:65], v[178:179]
	v_pk_mul_f32 v[180:181], v[54:55], v[180:181]
	v_pk_mul_f32 v[182:183], v[56:57], v[182:183]
	v_add_u32_e32 v66, s6, v149
	v_mad_i64_i32 v[66:67], s[50:51], v66, s16, v[142:143]
	v_lshl_add_u64 v[66:67], v[66:67], 0, s[48:49]
	v_lshl_add_u64 v[66:67], v[66:67], 0, s[26:27]
	v_mul_f32_e32 v58, v176, v58
	v_mul_f32_e32 v59, v177, v59
	v_mul_f32_e32 v60, v178, v60
	v_mul_f32_e32 v61, v179, v61
	v_mul_f32_e32 v62, v180, v50
	v_mul_f32_e32 v63, v181, v51
	v_lshl_add_u64 v[54:55], v[66:67], 0, v[0:1]
	v_mul_f32_e32 v56, v182, v52
	v_mul_f32_e32 v53, v183, v53
	v_cvt_pk_bf16_f32 v50, v58, v59
	v_cvt_pk_bf16_f32 v51, v60, v61
	v_cvt_pk_bf16_f32 v52, v62, v63
	v_cvt_pk_bf16_f32 v53, v56, v53
	global_store_dwordx4 v[54:55], v[50:53], off
	s_nop 1
	v_pk_mul_f32 v[176:177], v[46:47], v[184:185] op_sel_hi:[1,0]
	v_pk_mul_f32 v[178:179], v[48:49], v[184:185] op_sel_hi:[1,0]
	v_pk_mul_f32 v[180:181], v[38:39], v[184:185] op_sel_hi:[1,0]
	v_pk_mul_f32 v[182:183], v[40:41], v[184:185] op_sel_hi:[1,0]
	v_exp_f32_e32 v176, v176
	v_exp_f32_e32 v177, v177
	v_exp_f32_e32 v178, v178
	v_exp_f32_e32 v179, v179
	v_exp_f32_e32 v180, v180
	v_exp_f32_e32 v181, v181
	v_exp_f32_e32 v182, v182
	v_exp_f32_e32 v183, v183
	v_pk_add_f32 v[176:177], v[176:177], 1.0 op_sel_hi:[1,0]
	v_pk_add_f32 v[178:179], v[178:179], 1.0 op_sel_hi:[1,0]
	v_pk_add_f32 v[180:181], v[180:181], 1.0 op_sel_hi:[1,0]
	v_pk_add_f32 v[182:183], v[182:183], 1.0 op_sel_hi:[1,0]
	v_rcp_f32_e32 v176, v176
	v_rcp_f32_e32 v177, v177
	v_rcp_f32_e32 v178, v178
	v_rcp_f32_e32 v179, v179
	v_rcp_f32_e32 v180, v180
	v_rcp_f32_e32 v181, v181
	v_rcp_f32_e32 v182, v182
	v_rcp_f32_e32 v183, v183
	v_pk_mul_f32 v[176:177], v[46:47], v[176:177]
	v_pk_mul_f32 v[178:179], v[48:49], v[178:179]
	v_pk_mul_f32 v[180:181], v[38:39], v[180:181]
	v_pk_mul_f32 v[182:183], v[40:41], v[182:183]
	v_add_u32_e32 v50, s6, v150
	v_mad_i64_i32 v[50:51], s[50:51], v50, s16, v[142:143]
	v_lshl_add_u64 v[50:51], v[50:51], 0, s[48:49]
	v_lshl_add_u64 v[50:51], v[50:51], 0, s[26:27]
	v_mul_f32_e32 v42, v176, v42
	v_mul_f32_e32 v43, v177, v43
	v_mul_f32_e32 v44, v178, v44
	v_mul_f32_e32 v45, v179, v45
	v_mul_f32_e32 v46, v180, v34
	v_mul_f32_e32 v47, v181, v35
	v_lshl_add_u64 v[38:39], v[50:51], 0, v[0:1]
	v_mul_f32_e32 v40, v182, v36
	v_mul_f32_e32 v37, v183, v37
	v_cvt_pk_bf16_f32 v34, v42, v43
	v_cvt_pk_bf16_f32 v35, v44, v45
	v_cvt_pk_bf16_f32 v36, v46, v47
	v_cvt_pk_bf16_f32 v37, v40, v37
	global_store_dwordx4 v[38:39], v[34:37], off
	s_nop 1
	v_pk_mul_f32 v[176:177], v[30:31], v[184:185] op_sel_hi:[1,0]
	v_pk_mul_f32 v[178:179], v[32:33], v[184:185] op_sel_hi:[1,0]
	v_pk_mul_f32 v[180:181], v[22:23], v[184:185] op_sel_hi:[1,0]
	v_pk_mul_f32 v[182:183], v[24:25], v[184:185] op_sel_hi:[1,0]
	v_exp_f32_e32 v176, v176
	v_exp_f32_e32 v177, v177
	v_exp_f32_e32 v178, v178
	v_exp_f32_e32 v179, v179
	v_exp_f32_e32 v180, v180
	v_exp_f32_e32 v181, v181
	v_exp_f32_e32 v182, v182
	v_exp_f32_e32 v183, v183
	v_pk_add_f32 v[176:177], v[176:177], 1.0 op_sel_hi:[1,0]
	v_pk_add_f32 v[178:179], v[178:179], 1.0 op_sel_hi:[1,0]
	v_pk_add_f32 v[180:181], v[180:181], 1.0 op_sel_hi:[1,0]
	v_pk_add_f32 v[182:183], v[182:183], 1.0 op_sel_hi:[1,0]
	v_rcp_f32_e32 v176, v176
	v_rcp_f32_e32 v177, v177
	v_rcp_f32_e32 v178, v178
	v_rcp_f32_e32 v179, v179
	v_rcp_f32_e32 v180, v180
	v_rcp_f32_e32 v181, v181
	v_rcp_f32_e32 v182, v182
	v_rcp_f32_e32 v183, v183
	v_pk_mul_f32 v[176:177], v[30:31], v[176:177]
	v_pk_mul_f32 v[178:179], v[32:33], v[178:179]
	v_pk_mul_f32 v[180:181], v[22:23], v[180:181]
	v_pk_mul_f32 v[182:183], v[24:25], v[182:183]
	v_add_u32_e32 v34, s6, v151
	v_mad_i64_i32 v[34:35], s[50:51], v34, s16, v[142:143]
	v_lshl_add_u64 v[34:35], v[34:35], 0, s[48:49]
	v_lshl_add_u64 v[34:35], v[34:35], 0, s[26:27]
	v_mul_f32_e32 v26, v176, v26
	v_mul_f32_e32 v27, v177, v27
	v_mul_f32_e32 v28, v178, v28
	v_mul_f32_e32 v29, v179, v29
	v_mul_f32_e32 v30, v180, v18
	v_mul_f32_e32 v31, v181, v19
	v_lshl_add_u64 v[22:23], v[34:35], 0, v[0:1]
	v_mul_f32_e32 v24, v182, v20
	v_mul_f32_e32 v21, v183, v21
	v_cvt_pk_bf16_f32 v18, v26, v27
	v_cvt_pk_bf16_f32 v19, v28, v29
	v_cvt_pk_bf16_f32 v20, v30, v31
	v_cvt_pk_bf16_f32 v21, v24, v21
	global_store_dwordx4 v[22:23], v[18:21], off
	s_nop 1
	v_pk_mul_f32 v[176:177], v[14:15], v[184:185] op_sel_hi:[1,0]
	v_pk_mul_f32 v[178:179], v[16:17], v[184:185] op_sel_hi:[1,0]
	v_pk_mul_f32 v[180:181], v[6:7], v[184:185] op_sel_hi:[1,0]
	v_pk_mul_f32 v[182:183], v[8:9], v[184:185] op_sel_hi:[1,0]
	v_exp_f32_e32 v176, v176
	v_exp_f32_e32 v177, v177
	v_exp_f32_e32 v178, v178
	v_exp_f32_e32 v179, v179
	v_exp_f32_e32 v180, v180
	v_exp_f32_e32 v181, v181
	v_exp_f32_e32 v182, v182
	v_exp_f32_e32 v183, v183
	v_pk_add_f32 v[176:177], v[176:177], 1.0 op_sel_hi:[1,0]
	v_pk_add_f32 v[178:179], v[178:179], 1.0 op_sel_hi:[1,0]
	v_pk_add_f32 v[180:181], v[180:181], 1.0 op_sel_hi:[1,0]
	v_pk_add_f32 v[182:183], v[182:183], 1.0 op_sel_hi:[1,0]
	v_rcp_f32_e32 v176, v176
	v_rcp_f32_e32 v177, v177
	v_rcp_f32_e32 v178, v178
	v_rcp_f32_e32 v179, v179
	v_rcp_f32_e32 v180, v180
	v_rcp_f32_e32 v181, v181
	v_rcp_f32_e32 v182, v182
	v_rcp_f32_e32 v183, v183
	v_pk_mul_f32 v[176:177], v[14:15], v[176:177]
	v_pk_mul_f32 v[178:179], v[16:17], v[178:179]
	v_pk_mul_f32 v[180:181], v[6:7], v[180:181]
	v_pk_mul_f32 v[182:183], v[8:9], v[182:183]
	v_add_u32_e32 v18, s6, v152
	v_mad_i64_i32 v[18:19], s[50:51], v18, s16, v[142:143]
	v_lshl_add_u64 v[18:19], v[18:19], 0, s[48:49]
	v_lshl_add_u64 v[18:19], v[18:19], 0, s[26:27]
	s_mov_b64 s[48:49], -1
	v_mul_f32_e32 v10, v176, v10
	v_mul_f32_e32 v11, v177, v11
	v_mul_f32_e32 v12, v178, v12
	v_mul_f32_e32 v13, v179, v13
	v_mul_f32_e32 v14, v180, v2
	v_mul_f32_e32 v15, v181, v3
	v_lshl_add_u64 v[6:7], v[18:19], 0, v[0:1]
	v_mul_f32_e32 v8, v182, v4
	v_mul_f32_e32 v5, v183, v5
	v_cvt_pk_bf16_f32 v2, v10, v11
	v_cvt_pk_bf16_f32 v3, v12, v13
	v_cvt_pk_bf16_f32 v4, v14, v15
	v_cvt_pk_bf16_f32 v5, v8, v5
	global_store_dwordx4 v[6:7], v[2:5], off
	s_cbranch_vccnz .LBB0_428
	s_andn2_b64 vcc, exec, s[0:1]
	s_cbranch_vccnz .LBB0_427
	s_barrier
	s_branch .LBB0_427
